# gate (sigmoid) outputs stored with plain global_store instead of nt streaming stores
# speedup vs baseline: 1.0090x; 1.0090x over previous
; __device__ __forceinline__ u32x4 pack8(const f32x4 a, const f32x4 b) { u32x4 w; w.x = cvt_pk(a[0], a[1]); w.y = cvt_pk(a[2], a[3]); w.z = cvt_pk(b[0], b[1]); w.w = cvt_pk(b[2], b[3]); return w; }
; __device__ __forceinline__ f32x4 sigm4(f32x4 v) { f32x4 o; o[0] = sigm(v[0]); o[1] = sigm(v[1]); o[2] = sigm(v[2]); o[3] = sigm(v[3]); return o; }
; template <int NP> __device__ __forceinline__ float row_rstd(const float* ss, int row, int fq, float inv_dim, float eps) {
;     float s;
;     if constexpr (NP == 32) { const f32x4 a = *(const f32x4*)(ss + (size_t)row * 32 + fq * 8), b = *(const f32x4*)(ss + (size_t)row * 32 + fq * 8 + 4); s = ((a[0] + a[1]) + (a[2] + a[3])) + ((b[0] + b[1]) + (b[2] + b[3])); }
;     else if constexpr (NP == 8) { const f32x2 a = *(const f32x2*)(ss + (size_t)row * 8 + fq * 2); s = a[0] + a[1]; }
;     else { s = ss[(size_t)row * 4 + fq]; }
;     s += __shfl_xor(s, 16); s += __shfl_xor(s, 32);
;     return 1.0f / sqrtf(s * inv_dim + eps);
;     __device__ __forceinline__ void operator()(const f32x4 (&acc)[2][2][4][2], const Unit& u, int wr, int wc, int fr, int fq) const {
;     ...
;             const int row = rowb + ai * 128 + m * 16;
;             const float rs = rs_get<32>(rc, ssx, u.pm, wr * 64 + fr + ai * 128 + m * 16, fq, 1.0f / 2048.0f, 1e-6f);
;             bf16_t* d = sg + (size_t)row * 4096 + cb;
;             __builtin_nontemporal_store(pack8(sigm4(acc[ai][0][m][0] * rs), sigm4(acc[ai][0][m][1] * rs)), (u32x4*)d); __builtin_nontemporal_store(pack8(sigm4(acc[ai][1][m][0] * rs), sigm4(acc[ai][1][m][1] * rs)), (u32x4*)(d + 128));
.LBB0_315:
	s_waitcnt lgkmcnt(0)
	v_pk_mul_f32 v[126:127], v[126:127], v[146:147] op_sel_hi:[1,0]
	v_pk_mul_f32 v[122:123], v[122:123], v[146:147] op_sel_hi:[1,0]
	v_mul_f32_e32 v126, 0xbfb8aa3b, v126
	v_exp_f32_e32 v174, v126
	v_mul_f32_e32 v126, 0xbfb8aa3b, v127
	v_exp_f32_e32 v175, v126
	v_mul_f32_e32 v122, 0xbfb8aa3b, v122
	v_pk_mul_f32 v[126:127], v[128:129], v[146:147] op_sel_hi:[1,0]
	v_add_f32_e32 v128, 1.0, v174
	v_exp_f32_e32 v174, v122
	v_mul_f32_e32 v122, 0xbfb8aa3b, v123
	v_add_f32_e32 v129, 1.0, v175
	v_exp_f32_e32 v175, v122
	v_pk_mul_f32 v[122:123], v[124:125], v[146:147] op_sel_hi:[1,0]
	v_mul_f32_e32 v126, 0xbfb8aa3b, v126
	v_mul_f32_e32 v122, 0xbfb8aa3b, v122
	v_mul_f32_e32 v127, 0xbfb8aa3b, v127
	v_exp_f32_e32 v122, v122
	v_mul_f32_e32 v123, 0xbfb8aa3b, v123
	v_exp_f32_e32 v126, v126
	v_exp_f32_e32 v127, v127
	v_exp_f32_e32 v123, v123
	v_add_f32_e32 v122, 1.0, v122
	v_add_f32_e32 v126, 1.0, v126
	v_add_f32_e32 v127, 1.0, v127
	v_add_f32_e32 v124, 1.0, v174
	v_add_f32_e32 v125, 1.0, v175
	v_rcp_f32_e32 v174, v122
	v_add_f32_e32 v122, 1.0, v123
	v_rcp_f32_e32 v128, v128
	v_rcp_f32_e32 v129, v129
	v_rcp_f32_e32 v126, v126
	v_rcp_f32_e32 v127, v127
	v_rcp_f32_e32 v124, v124
	v_rcp_f32_e32 v125, v125
	v_rcp_f32_e32 v175, v122
	v_lshl_or_b32 v144, s83, 8, v172
	v_lshlrev_b64 v[166:167], 13, v[142:143]
	v_ashrrev_i32_e32 v145, 31, v144
	v_lshl_add_u64 v[166:167], s[26:27], 0, v[166:167]
	v_pk_mul_f32 v[118:119], v[118:119], v[146:147] op_sel_hi:[1,0]
	v_lshl_add_u64 v[166:167], v[144:145], 1, v[166:167]
	v_cvt_pk_bf16_f32 v122, v128, v129
	v_cvt_pk_bf16_f32 v123, v126, v127
	v_cvt_pk_bf16_f32 v124, v124, v125
	v_cvt_pk_bf16_f32 v125, v174, v175
	v_mul_f32_e32 v118, 0xbfb8aa3b, v118
	global_store_dwordx4 v[166:167], v[122:125], off
	v_pk_mul_f32 v[114:115], v[114:115], v[146:147] op_sel_hi:[1,0]
	s_andn2_b64 vcc, exec, s[8:9]
	v_exp_f32_e32 v122, v118
	v_mul_f32_e32 v118, 0xbfb8aa3b, v119
	v_exp_f32_e32 v123, v118
	v_mul_f32_e32 v114, 0xbfb8aa3b, v114
	v_pk_mul_f32 v[118:119], v[120:121], v[146:147] op_sel_hi:[1,0]
	v_add_f32_e32 v120, 1.0, v122
	v_exp_f32_e32 v122, v114
	v_mul_f32_e32 v114, 0xbfb8aa3b, v115
	v_add_f32_e32 v121, 1.0, v123
	v_exp_f32_e32 v123, v114
	v_pk_mul_f32 v[114:115], v[116:117], v[146:147] op_sel_hi:[1,0]
	v_mul_f32_e32 v118, 0xbfb8aa3b, v118
	v_mul_f32_e32 v114, 0xbfb8aa3b, v114
	v_mul_f32_e32 v119, 0xbfb8aa3b, v119
	v_exp_f32_e32 v114, v114
	v_mul_f32_e32 v115, 0xbfb8aa3b, v115
	v_exp_f32_e32 v118, v118
	v_exp_f32_e32 v119, v119
	v_exp_f32_e32 v115, v115
	v_add_f32_e32 v114, 1.0, v114
	v_add_f32_e32 v118, 1.0, v118
	v_add_f32_e32 v119, 1.0, v119
	v_add_f32_e32 v116, 1.0, v122
	v_add_f32_e32 v117, 1.0, v123
	v_rcp_f32_e32 v122, v114
	v_add_f32_e32 v114, 1.0, v115
	v_rcp_f32_e32 v120, v120
	v_rcp_f32_e32 v121, v121
	v_rcp_f32_e32 v118, v118
	v_rcp_f32_e32 v119, v119
	v_rcp_f32_e32 v116, v116
	v_rcp_f32_e32 v117, v117
	v_rcp_f32_e32 v123, v114
	v_cvt_pk_bf16_f32 v114, v120, v121
	v_cvt_pk_bf16_f32 v115, v118, v119
	v_cvt_pk_bf16_f32 v116, v116, v117
	v_cvt_pk_bf16_f32 v117, v122, v123
	global_store_dwordx4 v[166:167], v[114:117], off offset:256
	s_mov_b64 s[0:1], -1
	s_nop 0
	v_cndmask_b32_e64 v114, 0, 1, s[8:9]
	v_cmp_ne_u32_e64 s[40:41], 1, v114
	s_cbranch_vccnz .LBB0_317
	v_add_u32_e32 v114, s10, v149
	v_ashrrev_i32_e32 v115, 31, v114
	v_lshlrev_b64 v[114:115], 7, v[114:115]
	v_lshl_add_u64 v[118:119], v[136:137], 0, v[114:115]
	global_load_dwordx4 v[114:117], v[118:119], off
	s_nop 0
	global_load_dwordx4 v[118:121], v[118:119], off offset:16
	s_waitcnt vmcnt(0)
	v_mov_b32_e32 v122, v114
	v_mov_b32_e32 v123, v118
	v_mov_b32_e32 v118, v115
	v_pk_add_f32 v[114:115], v[122:123], v[118:119]
	v_mov_b32_e32 v118, v116
	v_mov_b32_e32 v119, v120
	v_mov_b32_e32 v120, v117
	v_pk_add_f32 v[116:117], v[118:119], v[120:121]
	s_nop 0
	v_pk_add_f32 v[114:115], v[114:115], v[116:117]
	v_and_b32_e32 v116, 64, v190
	v_add_f32_e32 v114, v114, v115
	v_xor_b32_e32 v115, 16, v190
	v_add_u32_e32 v116, 64, v116
	v_cmp_lt_i32_e32 vcc, v115, v116
	s_nop 1
	v_cndmask_b32_e32 v115, v190, v115, vcc
	v_lshlrev_b32_e32 v115, 2, v115
	ds_bpermute_b32 v115, v115, v114
	s_waitcnt lgkmcnt(0)
	v_add_f32_e32 v114, v114, v115
	v_xor_b32_e32 v115, 32, v190
	v_cmp_lt_i32_e32 vcc, v115, v116
	s_nop 1
	v_cndmask_b32_e32 v115, v190, v115, vcc
	v_lshlrev_b32_e32 v115, 2, v115
	ds_bpermute_b32 v115, v115, v114
	s_waitcnt lgkmcnt(0)
	v_add_f32_e32 v114, v114, v115
	v_fmamk_f32 v114, v114, 0x3a000000, v187
	v_cmp_gt_f32_e32 vcc, s3, v114
	v_mul_f32_e32 v115, 0x4f800000, v114
	s_nop 0
	v_cndmask_b32_e32 v114, v114, v115, vcc
	v_sqrt_f32_e32 v115, v114
	s_nop 0
	v_add_u32_e32 v116, -1, v115
	v_fma_f32 v117, -v116, v115, v114
	v_cmp_ge_f32_e64 s[0:1], 0, v117
	v_add_u32_e32 v117, 1, v115
	s_nop 0
	v_cndmask_b32_e64 v116, v115, v116, s[0:1]
	v_fma_f32 v115, -v117, v115, v114
	v_cmp_lt_f32_e64 s[0:1], 0, v115
	s_nop 1
	v_cndmask_b32_e64 v115, v116, v117, s[0:1]
	v_mul_f32_e32 v116, 0x37800000, v115
	v_cndmask_b32_e32 v115, v115, v116, vcc
	v_cmp_class_f32_e32 vcc, v114, v188
	s_nop 1
	v_cndmask_b32_e32 v114, v115, v114, vcc
	v_div_scale_f32 v115, s[0:1], v114, v114, 1.0
	v_rcp_f32_e32 v116, v115
	s_mov_b64 s[0:1], 0
	v_fma_f32 v117, -v115, v116, 1.0
	v_fmac_f32_e32 v116, v117, v116
	v_div_scale_f32 v117, vcc, 1.0, v114, 1.0
	v_mul_f32_e32 v118, v117, v116
	v_fma_f32 v119, -v115, v118, v117
	v_fmac_f32_e32 v118, v119, v116
	v_fma_f32 v115, -v115, v118, v117
	v_div_fmas_f32 v115, v115, v116, v118
	v_div_fixup_f32 v114, v115, v114, 1.0

; __device__ __forceinline__ u32x4 pack8(const f32x4 a, const f32x4 b) { u32x4 w; w.x = cvt_pk(a[0], a[1]); w.y = cvt_pk(a[2], a[3]); w.z = cvt_pk(b[0], b[1]); w.w = cvt_pk(b[2], b[3]); return w; }
; __device__ __forceinline__ f32x4 sigm4(f32x4 v) { f32x4 o; o[0] = sigm(v[0]); o[1] = sigm(v[1]); o[2] = sigm(v[2]); o[3] = sigm(v[3]); return o; }
; template <int NP> __device__ __forceinline__ float row_rstd(const float* ss, int row, int fq, float inv_dim, float eps) {
;     float s;
;     if constexpr (NP == 32) { const f32x4 a = *(const f32x4*)(ss + (size_t)row * 32 + fq * 8), b = *(const f32x4*)(ss + (size_t)row * 32 + fq * 8 + 4); s = ((a[0] + a[1]) + (a[2] + a[3])) + ((b[0] + b[1]) + (b[2] + b[3])); }
;     else if constexpr (NP == 8) { const f32x2 a = *(const f32x2*)(ss + (size_t)row * 8 + fq * 2); s = a[0] + a[1]; }
;     else { s = ss[(size_t)row * 4 + fq]; }
;     s += __shfl_xor(s, 16); s += __shfl_xor(s, 32);
;     return 1.0f / sqrtf(s * inv_dim + eps);
;     __device__ __forceinline__ void operator()(const f32x4 (&acc)[2][2][4][2], const Unit& u, int wr, int wc, int fr, int fq) const {
;     ...
;             const int row = rowb + ai * 128 + m * 16;
;             const float rs = rs_get<32>(rc, ssx, u.pm, wr * 64 + fr + ai * 128 + m * 16, fq, 1.0f / 2048.0f, 1e-6f);
;             bf16_t* d = sg + (size_t)row * 4096 + cb;
;             __builtin_nontemporal_store(pack8(sigm4(acc[ai][0][m][0] * rs), sigm4(acc[ai][0][m][1] * rs)), (u32x4*)d); __builtin_nontemporal_store(pack8(sigm4(acc[ai][1][m][0] * rs), sigm4(acc[ai][1][m][1] * rs)), (u32x4*)(d + 128));
.LBB0_319:
	s_waitcnt lgkmcnt(0)
	v_pk_mul_f32 v[110:111], v[110:111], v[114:115] op_sel_hi:[1,0]
	v_or_b32_e32 v116, 16, v142
	v_mul_f32_e32 v110, 0xbfb8aa3b, v110
	v_exp_f32_e32 v115, v110
	v_mul_f32_e32 v110, 0xbfb8aa3b, v111
	v_exp_f32_e32 v118, v110
	v_ashrrev_i32_e32 v117, 31, v116
	v_pk_mul_f32 v[106:107], v[106:107], v[114:115] op_sel_hi:[1,0]
	v_pk_mul_f32 v[110:111], v[112:113], v[114:115] op_sel_hi:[1,0]
	v_mul_f32_e32 v106, 0xbfb8aa3b, v106
	v_add_f32_e32 v112, 1.0, v115
	v_exp_f32_e32 v115, v106
	v_mul_f32_e32 v106, 0xbfb8aa3b, v107
	v_add_f32_e32 v113, 1.0, v118
	v_exp_f32_e32 v118, v106
	v_pk_mul_f32 v[106:107], v[108:109], v[114:115] op_sel_hi:[1,0]
	v_mul_f32_e32 v110, 0xbfb8aa3b, v110
	v_mul_f32_e32 v106, 0xbfb8aa3b, v106
	v_mul_f32_e32 v111, 0xbfb8aa3b, v111
	v_exp_f32_e32 v106, v106
	v_mul_f32_e32 v107, 0xbfb8aa3b, v107
	v_exp_f32_e32 v110, v110
	v_exp_f32_e32 v111, v111
	v_exp_f32_e32 v107, v107
	v_add_f32_e32 v106, 1.0, v106
	v_add_f32_e32 v110, 1.0, v110
	v_add_f32_e32 v111, 1.0, v111
	v_add_f32_e32 v108, 1.0, v115
	v_add_f32_e32 v109, 1.0, v118
	v_rcp_f32_e32 v115, v106
	v_add_f32_e32 v106, 1.0, v107
	v_rcp_f32_e32 v112, v112
	v_rcp_f32_e32 v113, v113
	v_rcp_f32_e32 v110, v110
	v_rcp_f32_e32 v111, v111
	v_rcp_f32_e32 v108, v108
	v_rcp_f32_e32 v109, v109
	v_rcp_f32_e32 v118, v106
	v_lshlrev_b64 v[116:117], 13, v[116:117]
	v_lshl_add_u64 v[116:117], s[26:27], 0, v[116:117]
	v_pk_mul_f32 v[102:103], v[102:103], v[114:115] op_sel_hi:[1,0]
	v_lshl_add_u64 v[116:117], v[144:145], 1, v[116:117]
	v_cvt_pk_bf16_f32 v106, v112, v113
	v_cvt_pk_bf16_f32 v107, v110, v111
	v_cvt_pk_bf16_f32 v108, v108, v109
	v_cvt_pk_bf16_f32 v109, v115, v118
	v_mul_f32_e32 v102, 0xbfb8aa3b, v102
	global_store_dwordx4 v[116:117], v[106:109], off
	v_pk_mul_f32 v[98:99], v[98:99], v[114:115] op_sel_hi:[1,0]
	s_and_b64 vcc, exec, s[40:41]
	v_exp_f32_e32 v106, v102
	v_mul_f32_e32 v102, 0xbfb8aa3b, v103
	v_exp_f32_e32 v107, v102
	v_mul_f32_e32 v98, 0xbfb8aa3b, v98
	v_pk_mul_f32 v[102:103], v[104:105], v[114:115] op_sel_hi:[1,0]
	v_add_f32_e32 v104, 1.0, v106
	v_exp_f32_e32 v106, v98
	v_mul_f32_e32 v98, 0xbfb8aa3b, v99
	v_add_f32_e32 v105, 1.0, v107
	v_exp_f32_e32 v107, v98
	v_pk_mul_f32 v[98:99], v[100:101], v[114:115] op_sel_hi:[1,0]
	v_mul_f32_e32 v102, 0xbfb8aa3b, v102
	v_mul_f32_e32 v98, 0xbfb8aa3b, v98
	v_mul_f32_e32 v103, 0xbfb8aa3b, v103
	v_exp_f32_e32 v98, v98
	v_mul_f32_e32 v99, 0xbfb8aa3b, v99
	v_exp_f32_e32 v102, v102
	v_exp_f32_e32 v103, v103
	v_exp_f32_e32 v99, v99
	v_add_f32_e32 v98, 1.0, v98
	v_add_f32_e32 v102, 1.0, v102
	v_add_f32_e32 v103, 1.0, v103
	v_add_f32_e32 v100, 1.0, v106
	v_add_f32_e32 v101, 1.0, v107
	v_rcp_f32_e32 v106, v98
	v_add_f32_e32 v98, 1.0, v99
	v_rcp_f32_e32 v104, v104
	v_rcp_f32_e32 v105, v105
	v_rcp_f32_e32 v102, v102
	v_rcp_f32_e32 v103, v103
	v_rcp_f32_e32 v100, v100
	v_rcp_f32_e32 v101, v101
	v_rcp_f32_e32 v107, v98
	v_cvt_pk_bf16_f32 v98, v104, v105
	v_cvt_pk_bf16_f32 v99, v102, v103
	v_cvt_pk_bf16_f32 v100, v100, v101
	v_cvt_pk_bf16_f32 v101, v106, v107
	s_mov_b64 s[0:1], -1
	global_store_dwordx4 v[116:117], v[98:101], off offset:256
	s_cbranch_vccnz .LBB0_321
	s_nop 0
	v_add_u32_e32 v98, s10, v150
	v_ashrrev_i32_e32 v99, 31, v98
	v_lshlrev_b64 v[98:99], 7, v[98:99]
	v_lshl_add_u64 v[102:103], v[136:137], 0, v[98:99]
	global_load_dwordx4 v[98:101], v[102:103], off
	s_nop 0
	global_load_dwordx4 v[102:105], v[102:103], off offset:16
	s_waitcnt vmcnt(0)
	v_mov_b32_e32 v106, v98
	v_mov_b32_e32 v107, v102
	v_mov_b32_e32 v102, v99
	v_pk_add_f32 v[98:99], v[106:107], v[102:103]
	v_mov_b32_e32 v102, v100
	v_mov_b32_e32 v103, v104
	v_mov_b32_e32 v104, v101
	v_pk_add_f32 v[100:101], v[102:103], v[104:105]
	s_nop 0
	v_pk_add_f32 v[98:99], v[98:99], v[100:101]
	v_and_b32_e32 v100, 64, v190
	v_add_f32_e32 v98, v98, v99
	v_xor_b32_e32 v99, 16, v190
	v_add_u32_e32 v100, 64, v100
	v_cmp_lt_i32_e32 vcc, v99, v100
	s_nop 1
	v_cndmask_b32_e32 v99, v190, v99, vcc
	v_lshlrev_b32_e32 v99, 2, v99
	ds_bpermute_b32 v99, v99, v98
	s_waitcnt lgkmcnt(0)
	v_add_f32_e32 v98, v98, v99
	v_xor_b32_e32 v99, 32, v190
	v_cmp_lt_i32_e32 vcc, v99, v100
	s_nop 1
	v_cndmask_b32_e32 v99, v190, v99, vcc
	v_lshlrev_b32_e32 v99, 2, v99
	ds_bpermute_b32 v99, v99, v98
	s_waitcnt lgkmcnt(0)
	v_add_f32_e32 v98, v98, v99
	v_fmamk_f32 v98, v98, 0x3a000000, v187
	v_cmp_gt_f32_e32 vcc, s3, v98
	v_mul_f32_e32 v99, 0x4f800000, v98
	s_nop 0
	v_cndmask_b32_e32 v98, v98, v99, vcc
	v_sqrt_f32_e32 v99, v98
	s_nop 0
	v_add_u32_e32 v100, -1, v99
	v_fma_f32 v101, -v100, v99, v98
	v_cmp_ge_f32_e64 s[0:1], 0, v101
	v_add_u32_e32 v101, 1, v99
	s_nop 0
	v_cndmask_b32_e64 v100, v99, v100, s[0:1]
	v_fma_f32 v99, -v101, v99, v98
	v_cmp_lt_f32_e64 s[0:1], 0, v99
	s_nop 1
	v_cndmask_b32_e64 v99, v100, v101, s[0:1]
	v_mul_f32_e32 v100, 0x37800000, v99
	v_cndmask_b32_e32 v99, v99, v100, vcc
	v_cmp_class_f32_e32 vcc, v98, v188
	s_nop 1
	v_cndmask_b32_e32 v98, v99, v98, vcc
	v_div_scale_f32 v99, s[0:1], v98, v98, 1.0
	v_rcp_f32_e32 v100, v99
	s_mov_b64 s[0:1], 0
	v_fma_f32 v101, -v99, v100, 1.0
	v_fmac_f32_e32 v100, v101, v100
	v_div_scale_f32 v101, vcc, 1.0, v98, 1.0
	v_mul_f32_e32 v102, v101, v100
	v_fma_f32 v103, -v99, v102, v101
	v_fmac_f32_e32 v102, v103, v100
	v_fma_f32 v99, -v99, v102, v101
	v_div_fmas_f32 v99, v99, v100, v102
	v_div_fixup_f32 v98, v99, v98, 1.0

; __device__ __forceinline__ u32x4 pack8(const f32x4 a, const f32x4 b) { u32x4 w; w.x = cvt_pk(a[0], a[1]); w.y = cvt_pk(a[2], a[3]); w.z = cvt_pk(b[0], b[1]); w.w = cvt_pk(b[2], b[3]); return w; }
; __device__ __forceinline__ f32x4 sigm4(f32x4 v) { f32x4 o; o[0] = sigm(v[0]); o[1] = sigm(v[1]); o[2] = sigm(v[2]); o[3] = sigm(v[3]); return o; }
; template <int NP> __device__ __forceinline__ float row_rstd(const float* ss, int row, int fq, float inv_dim, float eps) {
;     float s;
;     if constexpr (NP == 32) { const f32x4 a = *(const f32x4*)(ss + (size_t)row * 32 + fq * 8), b = *(const f32x4*)(ss + (size_t)row * 32 + fq * 8 + 4); s = ((a[0] + a[1]) + (a[2] + a[3])) + ((b[0] + b[1]) + (b[2] + b[3])); }
;     else if constexpr (NP == 8) { const f32x2 a = *(const f32x2*)(ss + (size_t)row * 8 + fq * 2); s = a[0] + a[1]; }
;     else { s = ss[(size_t)row * 4 + fq]; }
;     s += __shfl_xor(s, 16); s += __shfl_xor(s, 32);
;     return 1.0f / sqrtf(s * inv_dim + eps);
;     __device__ __forceinline__ void operator()(const f32x4 (&acc)[2][2][4][2], const Unit& u, int wr, int wc, int fr, int fq) const {
;     ...
;             const int row = rowb + ai * 128 + m * 16;
;             const float rs = rs_get<32>(rc, ssx, u.pm, wr * 64 + fr + ai * 128 + m * 16, fq, 1.0f / 2048.0f, 1e-6f);
;             bf16_t* d = sg + (size_t)row * 4096 + cb;
;             __builtin_nontemporal_store(pack8(sigm4(acc[ai][0][m][0] * rs), sigm4(acc[ai][0][m][1] * rs)), (u32x4*)d); __builtin_nontemporal_store(pack8(sigm4(acc[ai][1][m][0] * rs), sigm4(acc[ai][1][m][1] * rs)), (u32x4*)(d + 128));
.LBB0_323:
	s_waitcnt lgkmcnt(0)
	v_pk_mul_f32 v[94:95], v[94:95], v[98:99] op_sel_hi:[1,0]
	v_or_b32_e32 v100, 32, v142
	v_mul_f32_e32 v94, 0xbfb8aa3b, v94
	v_exp_f32_e32 v99, v94
	v_mul_f32_e32 v94, 0xbfb8aa3b, v95
	v_exp_f32_e32 v102, v94
	v_ashrrev_i32_e32 v101, 31, v100
	v_pk_mul_f32 v[90:91], v[90:91], v[98:99] op_sel_hi:[1,0]
	v_pk_mul_f32 v[94:95], v[96:97], v[98:99] op_sel_hi:[1,0]
	v_mul_f32_e32 v90, 0xbfb8aa3b, v90
	v_add_f32_e32 v96, 1.0, v99
	v_exp_f32_e32 v99, v90
	v_mul_f32_e32 v90, 0xbfb8aa3b, v91
	v_add_f32_e32 v97, 1.0, v102
	v_exp_f32_e32 v102, v90
	v_pk_mul_f32 v[90:91], v[92:93], v[98:99] op_sel_hi:[1,0]
	v_mul_f32_e32 v94, 0xbfb8aa3b, v94
	v_mul_f32_e32 v90, 0xbfb8aa3b, v90
	v_mul_f32_e32 v95, 0xbfb8aa3b, v95
	v_exp_f32_e32 v90, v90
	v_mul_f32_e32 v91, 0xbfb8aa3b, v91
	v_exp_f32_e32 v94, v94
	v_exp_f32_e32 v95, v95
	v_exp_f32_e32 v91, v91
	v_add_f32_e32 v90, 1.0, v90
	v_add_f32_e32 v94, 1.0, v94
	v_add_f32_e32 v95, 1.0, v95
	v_add_f32_e32 v92, 1.0, v99
	v_add_f32_e32 v93, 1.0, v102
	v_rcp_f32_e32 v99, v90
	v_add_f32_e32 v90, 1.0, v91
	v_rcp_f32_e32 v96, v96
	v_rcp_f32_e32 v97, v97
	v_rcp_f32_e32 v94, v94
	v_rcp_f32_e32 v95, v95
	v_rcp_f32_e32 v92, v92
	v_rcp_f32_e32 v93, v93
	v_rcp_f32_e32 v102, v90
	v_lshlrev_b64 v[100:101], 13, v[100:101]
	v_lshl_add_u64 v[100:101], s[26:27], 0, v[100:101]
	v_pk_mul_f32 v[86:87], v[86:87], v[98:99] op_sel_hi:[1,0]
	v_lshl_add_u64 v[100:101], v[144:145], 1, v[100:101]
	v_cvt_pk_bf16_f32 v90, v96, v97
	v_cvt_pk_bf16_f32 v91, v94, v95
	v_cvt_pk_bf16_f32 v92, v92, v93
	v_cvt_pk_bf16_f32 v93, v99, v102
	v_mul_f32_e32 v86, 0xbfb8aa3b, v86
	global_store_dwordx4 v[100:101], v[90:93], off
	v_pk_mul_f32 v[82:83], v[82:83], v[98:99] op_sel_hi:[1,0]
	s_and_b64 vcc, exec, s[40:41]
	v_exp_f32_e32 v90, v86
	v_mul_f32_e32 v86, 0xbfb8aa3b, v87
	v_exp_f32_e32 v91, v86
	v_mul_f32_e32 v82, 0xbfb8aa3b, v82
	v_pk_mul_f32 v[86:87], v[88:89], v[98:99] op_sel_hi:[1,0]
	v_add_f32_e32 v88, 1.0, v90
	v_exp_f32_e32 v90, v82
	v_mul_f32_e32 v82, 0xbfb8aa3b, v83
	v_add_f32_e32 v89, 1.0, v91
	v_exp_f32_e32 v91, v82
	v_pk_mul_f32 v[82:83], v[84:85], v[98:99] op_sel_hi:[1,0]
	v_mul_f32_e32 v86, 0xbfb8aa3b, v86
	v_mul_f32_e32 v82, 0xbfb8aa3b, v82
	v_mul_f32_e32 v87, 0xbfb8aa3b, v87
	v_exp_f32_e32 v82, v82
	v_mul_f32_e32 v83, 0xbfb8aa3b, v83
	v_exp_f32_e32 v86, v86
	v_exp_f32_e32 v87, v87
	v_exp_f32_e32 v83, v83
	v_add_f32_e32 v82, 1.0, v82
	v_add_f32_e32 v86, 1.0, v86
	v_add_f32_e32 v87, 1.0, v87
	v_add_f32_e32 v84, 1.0, v90
	v_add_f32_e32 v85, 1.0, v91
	v_rcp_f32_e32 v90, v82
	v_add_f32_e32 v82, 1.0, v83
	v_rcp_f32_e32 v88, v88
	v_rcp_f32_e32 v89, v89
	v_rcp_f32_e32 v86, v86
	v_rcp_f32_e32 v87, v87
	v_rcp_f32_e32 v84, v84
	v_rcp_f32_e32 v85, v85
	v_rcp_f32_e32 v91, v82
	v_cvt_pk_bf16_f32 v82, v88, v89
	v_cvt_pk_bf16_f32 v83, v86, v87
	v_cvt_pk_bf16_f32 v84, v84, v85
	v_cvt_pk_bf16_f32 v85, v90, v91
	s_mov_b64 s[0:1], -1
	global_store_dwordx4 v[100:101], v[82:85], off offset:256
	s_cbranch_vccnz .LBB0_325
	s_nop 0
	v_add_u32_e32 v82, s10, v151
	v_ashrrev_i32_e32 v83, 31, v82
	v_lshlrev_b64 v[82:83], 7, v[82:83]
	v_lshl_add_u64 v[86:87], v[136:137], 0, v[82:83]
	global_load_dwordx4 v[82:85], v[86:87], off
	s_nop 0
	global_load_dwordx4 v[86:89], v[86:87], off offset:16
	s_waitcnt vmcnt(0)
	v_mov_b32_e32 v90, v82
	v_mov_b32_e32 v91, v86
	v_mov_b32_e32 v86, v83
	v_pk_add_f32 v[82:83], v[90:91], v[86:87]
	v_mov_b32_e32 v86, v84
	v_mov_b32_e32 v87, v88
	v_mov_b32_e32 v88, v85
	v_pk_add_f32 v[84:85], v[86:87], v[88:89]
	s_nop 0
	v_pk_add_f32 v[82:83], v[82:83], v[84:85]
	v_and_b32_e32 v84, 64, v190
	v_add_f32_e32 v82, v82, v83
	v_xor_b32_e32 v83, 16, v190
	v_add_u32_e32 v84, 64, v84
	v_cmp_lt_i32_e32 vcc, v83, v84
	s_nop 1
	v_cndmask_b32_e32 v83, v190, v83, vcc
	v_lshlrev_b32_e32 v83, 2, v83
	ds_bpermute_b32 v83, v83, v82
	s_waitcnt lgkmcnt(0)
	v_add_f32_e32 v82, v82, v83
	v_xor_b32_e32 v83, 32, v190
	v_cmp_lt_i32_e32 vcc, v83, v84
	s_nop 1
	v_cndmask_b32_e32 v83, v190, v83, vcc
	v_lshlrev_b32_e32 v83, 2, v83
	ds_bpermute_b32 v83, v83, v82
	s_waitcnt lgkmcnt(0)
	v_add_f32_e32 v82, v82, v83
	v_fmamk_f32 v82, v82, 0x3a000000, v187
	v_cmp_gt_f32_e32 vcc, s3, v82
	v_mul_f32_e32 v83, 0x4f800000, v82
	s_nop 0
	v_cndmask_b32_e32 v82, v82, v83, vcc
	v_sqrt_f32_e32 v83, v82
	s_nop 0
	v_add_u32_e32 v84, -1, v83
	v_fma_f32 v85, -v84, v83, v82
	v_cmp_ge_f32_e64 s[0:1], 0, v85
	v_add_u32_e32 v85, 1, v83
	s_nop 0
	v_cndmask_b32_e64 v84, v83, v84, s[0:1]
	v_fma_f32 v83, -v85, v83, v82
	v_cmp_lt_f32_e64 s[0:1], 0, v83
	s_nop 1
	v_cndmask_b32_e64 v83, v84, v85, s[0:1]
	v_mul_f32_e32 v84, 0x37800000, v83
	v_cndmask_b32_e32 v83, v83, v84, vcc
	v_cmp_class_f32_e32 vcc, v82, v188
	s_nop 1
	v_cndmask_b32_e32 v82, v83, v82, vcc
	v_div_scale_f32 v83, s[0:1], v82, v82, 1.0
	v_rcp_f32_e32 v84, v83
	s_mov_b64 s[0:1], 0
	v_fma_f32 v85, -v83, v84, 1.0
	v_fmac_f32_e32 v84, v85, v84
	v_div_scale_f32 v85, vcc, 1.0, v82, 1.0
	v_mul_f32_e32 v86, v85, v84
	v_fma_f32 v87, -v83, v86, v85
	v_fmac_f32_e32 v86, v87, v84
	v_fma_f32 v83, -v83, v86, v85
	v_div_fmas_f32 v83, v83, v84, v86
	v_div_fixup_f32 v82, v83, v82, 1.0

; __device__ __forceinline__ u32x4 pack8(const f32x4 a, const f32x4 b) { u32x4 w; w.x = cvt_pk(a[0], a[1]); w.y = cvt_pk(a[2], a[3]); w.z = cvt_pk(b[0], b[1]); w.w = cvt_pk(b[2], b[3]); return w; }
; __device__ __forceinline__ f32x4 sigm4(f32x4 v) { f32x4 o; o[0] = sigm(v[0]); o[1] = sigm(v[1]); o[2] = sigm(v[2]); o[3] = sigm(v[3]); return o; }
; template <int NP> __device__ __forceinline__ float row_rstd(const float* ss, int row, int fq, float inv_dim, float eps) {
;     float s;
;     if constexpr (NP == 32) { const f32x4 a = *(const f32x4*)(ss + (size_t)row * 32 + fq * 8), b = *(const f32x4*)(ss + (size_t)row * 32 + fq * 8 + 4); s = ((a[0] + a[1]) + (a[2] + a[3])) + ((b[0] + b[1]) + (b[2] + b[3])); }
;     else if constexpr (NP == 8) { const f32x2 a = *(const f32x2*)(ss + (size_t)row * 8 + fq * 2); s = a[0] + a[1]; }
;     else { s = ss[(size_t)row * 4 + fq]; }
;     s += __shfl_xor(s, 16); s += __shfl_xor(s, 32);
;     return 1.0f / sqrtf(s * inv_dim + eps);
;     __device__ __forceinline__ void operator()(const f32x4 (&acc)[2][2][4][2], const Unit& u, int wr, int wc, int fr, int fq) const {
;     ...
;             const int row = rowb + ai * 128 + m * 16;
;             const float rs = rs_get<32>(rc, ssx, u.pm, wr * 64 + fr + ai * 128 + m * 16, fq, 1.0f / 2048.0f, 1e-6f);
;             bf16_t* d = sg + (size_t)row * 4096 + cb;
;             __builtin_nontemporal_store(pack8(sigm4(acc[ai][0][m][0] * rs), sigm4(acc[ai][0][m][1] * rs)), (u32x4*)d); __builtin_nontemporal_store(pack8(sigm4(acc[ai][1][m][0] * rs), sigm4(acc[ai][1][m][1] * rs)), (u32x4*)(d + 128));
.LBB0_327:
	s_waitcnt lgkmcnt(0)
	v_pk_mul_f32 v[78:79], v[78:79], v[82:83] op_sel_hi:[1,0]
	v_or_b32_e32 v84, 48, v142
	v_mul_f32_e32 v78, 0xbfb8aa3b, v78
	v_exp_f32_e32 v83, v78
	v_mul_f32_e32 v78, 0xbfb8aa3b, v79
	v_exp_f32_e32 v86, v78
	v_ashrrev_i32_e32 v85, 31, v84
	v_pk_mul_f32 v[74:75], v[74:75], v[82:83] op_sel_hi:[1,0]
	v_pk_mul_f32 v[78:79], v[80:81], v[82:83] op_sel_hi:[1,0]
	v_mul_f32_e32 v74, 0xbfb8aa3b, v74
	v_add_f32_e32 v80, 1.0, v83
	v_exp_f32_e32 v83, v74
	v_mul_f32_e32 v74, 0xbfb8aa3b, v75
	v_add_f32_e32 v81, 1.0, v86
	v_exp_f32_e32 v86, v74
	v_pk_mul_f32 v[74:75], v[76:77], v[82:83] op_sel_hi:[1,0]
	v_mul_f32_e32 v78, 0xbfb8aa3b, v78
	v_mul_f32_e32 v74, 0xbfb8aa3b, v74
	v_mul_f32_e32 v79, 0xbfb8aa3b, v79
	v_exp_f32_e32 v74, v74
	v_mul_f32_e32 v75, 0xbfb8aa3b, v75
	v_exp_f32_e32 v78, v78
	v_exp_f32_e32 v79, v79
	v_exp_f32_e32 v75, v75
	v_add_f32_e32 v74, 1.0, v74
	v_add_f32_e32 v78, 1.0, v78
	v_add_f32_e32 v79, 1.0, v79
	v_add_f32_e32 v76, 1.0, v83
	v_add_f32_e32 v77, 1.0, v86
	v_rcp_f32_e32 v83, v74
	v_add_f32_e32 v74, 1.0, v75
	v_rcp_f32_e32 v80, v80
	v_rcp_f32_e32 v81, v81
	v_rcp_f32_e32 v78, v78
	v_rcp_f32_e32 v79, v79
	v_rcp_f32_e32 v76, v76
	v_rcp_f32_e32 v77, v77
	v_rcp_f32_e32 v86, v74
	v_lshlrev_b64 v[84:85], 13, v[84:85]
	v_lshl_add_u64 v[84:85], s[26:27], 0, v[84:85]
	v_pk_mul_f32 v[70:71], v[70:71], v[82:83] op_sel_hi:[1,0]
	v_lshl_add_u64 v[84:85], v[144:145], 1, v[84:85]
	v_cvt_pk_bf16_f32 v74, v80, v81
	v_cvt_pk_bf16_f32 v75, v78, v79
	v_cvt_pk_bf16_f32 v76, v76, v77
	v_cvt_pk_bf16_f32 v77, v83, v86
	v_mul_f32_e32 v70, 0xbfb8aa3b, v70
	global_store_dwordx4 v[84:85], v[74:77], off
	v_pk_mul_f32 v[66:67], v[66:67], v[82:83] op_sel_hi:[1,0]
	s_and_b64 vcc, exec, s[40:41]
	v_exp_f32_e32 v74, v70
	v_mul_f32_e32 v70, 0xbfb8aa3b, v71
	v_exp_f32_e32 v75, v70
	v_mul_f32_e32 v66, 0xbfb8aa3b, v66
	v_pk_mul_f32 v[70:71], v[72:73], v[82:83] op_sel_hi:[1,0]
	v_add_f32_e32 v72, 1.0, v74
	v_exp_f32_e32 v74, v66
	v_mul_f32_e32 v66, 0xbfb8aa3b, v67
	v_add_f32_e32 v73, 1.0, v75
	v_exp_f32_e32 v75, v66
	v_pk_mul_f32 v[66:67], v[68:69], v[82:83] op_sel_hi:[1,0]
	v_mul_f32_e32 v70, 0xbfb8aa3b, v70
	v_mul_f32_e32 v66, 0xbfb8aa3b, v66
	v_mul_f32_e32 v71, 0xbfb8aa3b, v71
	v_exp_f32_e32 v66, v66
	v_mul_f32_e32 v67, 0xbfb8aa3b, v67
	v_exp_f32_e32 v70, v70
	v_exp_f32_e32 v71, v71
	v_exp_f32_e32 v67, v67
	v_add_f32_e32 v66, 1.0, v66
	v_add_f32_e32 v70, 1.0, v70
	v_add_f32_e32 v71, 1.0, v71
	v_add_f32_e32 v68, 1.0, v74
	v_add_f32_e32 v69, 1.0, v75
	v_rcp_f32_e32 v74, v66
	v_add_f32_e32 v66, 1.0, v67
	v_rcp_f32_e32 v72, v72
	v_rcp_f32_e32 v73, v73
	v_rcp_f32_e32 v70, v70
	v_rcp_f32_e32 v71, v71
	v_rcp_f32_e32 v68, v68
	v_rcp_f32_e32 v69, v69
	v_rcp_f32_e32 v75, v66
	v_cvt_pk_bf16_f32 v66, v72, v73
	v_cvt_pk_bf16_f32 v67, v70, v71
	v_cvt_pk_bf16_f32 v68, v68, v69
	v_cvt_pk_bf16_f32 v69, v74, v75
	global_store_dwordx4 v[84:85], v[66:69], off offset:256
	s_mov_b64 s[0:1], -1
	s_cbranch_vccnz .LBB0_329
	v_add_u32_e32 v66, s10, v152
	v_ashrrev_i32_e32 v67, 31, v66
	v_lshlrev_b64 v[66:67], 7, v[66:67]
	v_lshl_add_u64 v[70:71], v[136:137], 0, v[66:67]
	global_load_dwordx4 v[66:69], v[70:71], off
	s_nop 0
	global_load_dwordx4 v[70:73], v[70:71], off offset:16
	s_waitcnt vmcnt(0)
	v_mov_b32_e32 v74, v66
	v_mov_b32_e32 v75, v70
	v_mov_b32_e32 v70, v67
	v_pk_add_f32 v[66:67], v[74:75], v[70:71]
	v_mov_b32_e32 v70, v68
	v_mov_b32_e32 v71, v72
	v_mov_b32_e32 v72, v69
	v_pk_add_f32 v[68:69], v[70:71], v[72:73]
	s_nop 0
	v_pk_add_f32 v[66:67], v[66:67], v[68:69]
	v_and_b32_e32 v68, 64, v190
	v_add_f32_e32 v66, v66, v67
	v_xor_b32_e32 v67, 16, v190
	v_add_u32_e32 v68, 64, v68
	v_cmp_lt_i32_e32 vcc, v67, v68
	s_nop 1
	v_cndmask_b32_e32 v67, v190, v67, vcc
	v_lshlrev_b32_e32 v67, 2, v67
	ds_bpermute_b32 v67, v67, v66
	s_waitcnt lgkmcnt(0)
	v_add_f32_e32 v66, v66, v67
	v_xor_b32_e32 v67, 32, v190
	v_cmp_lt_i32_e32 vcc, v67, v68
	s_nop 1
	v_cndmask_b32_e32 v67, v190, v67, vcc
	v_lshlrev_b32_e32 v67, 2, v67
	ds_bpermute_b32 v67, v67, v66
	s_waitcnt lgkmcnt(0)
	v_add_f32_e32 v66, v66, v67
	v_fmamk_f32 v66, v66, 0x3a000000, v187
	v_cmp_gt_f32_e32 vcc, s3, v66
	v_mul_f32_e32 v67, 0x4f800000, v66
	s_nop 0
	v_cndmask_b32_e32 v66, v66, v67, vcc
	v_sqrt_f32_e32 v67, v66
	s_nop 0
	v_add_u32_e32 v68, -1, v67
	v_fma_f32 v69, -v68, v67, v66
	v_cmp_ge_f32_e64 s[0:1], 0, v69
	v_add_u32_e32 v69, 1, v67
	s_nop 0
	v_cndmask_b32_e64 v68, v67, v68, s[0:1]
	v_fma_f32 v67, -v69, v67, v66
	v_cmp_lt_f32_e64 s[0:1], 0, v67
	s_nop 1
	v_cndmask_b32_e64 v67, v68, v69, s[0:1]
	v_mul_f32_e32 v68, 0x37800000, v67
	v_cndmask_b32_e32 v67, v67, v68, vcc
	v_cmp_class_f32_e32 vcc, v66, v188
	s_nop 1
	v_cndmask_b32_e32 v66, v67, v66, vcc
	v_div_scale_f32 v67, s[0:1], v66, v66, 1.0
	v_rcp_f32_e32 v68, v67
	s_mov_b64 s[0:1], 0
	v_fma_f32 v69, -v67, v68, 1.0
	v_fmac_f32_e32 v68, v69, v68
	v_div_scale_f32 v69, vcc, 1.0, v66, 1.0
	v_mul_f32_e32 v70, v69, v68
	v_fma_f32 v71, -v67, v70, v69
	v_fmac_f32_e32 v70, v71, v68
	v_fma_f32 v67, -v67, v70, v69
	v_div_fmas_f32 v67, v67, v68, v70
	v_div_fixup_f32 v66, v67, v66, 1.0

; __device__ __forceinline__ u32x4 pack8(const f32x4 a, const f32x4 b) { u32x4 w; w.x = cvt_pk(a[0], a[1]); w.y = cvt_pk(a[2], a[3]); w.z = cvt_pk(b[0], b[1]); w.w = cvt_pk(b[2], b[3]); return w; }
; __device__ __forceinline__ f32x4 sigm4(f32x4 v) { f32x4 o; o[0] = sigm(v[0]); o[1] = sigm(v[1]); o[2] = sigm(v[2]); o[3] = sigm(v[3]); return o; }
; template <int NP> __device__ __forceinline__ float row_rstd(const float* ss, int row, int fq, float inv_dim, float eps) {
;     float s;
;     if constexpr (NP == 32) { const f32x4 a = *(const f32x4*)(ss + (size_t)row * 32 + fq * 8), b = *(const f32x4*)(ss + (size_t)row * 32 + fq * 8 + 4); s = ((a[0] + a[1]) + (a[2] + a[3])) + ((b[0] + b[1]) + (b[2] + b[3])); }
;     else if constexpr (NP == 8) { const f32x2 a = *(const f32x2*)(ss + (size_t)row * 8 + fq * 2); s = a[0] + a[1]; }
;     else { s = ss[(size_t)row * 4 + fq]; }
;     s += __shfl_xor(s, 16); s += __shfl_xor(s, 32);
;     return 1.0f / sqrtf(s * inv_dim + eps);
;     __device__ __forceinline__ void operator()(const f32x4 (&acc)[2][2][4][2], const Unit& u, int wr, int wc, int fr, int fq) const {
;     ...
;             const int row = rowb + ai * 128 + m * 16;
;             const float rs = rs_get<32>(rc, ssx, u.pm, wr * 64 + fr + ai * 128 + m * 16, fq, 1.0f / 2048.0f, 1e-6f);
;             bf16_t* d = sg + (size_t)row * 4096 + cb;
;             __builtin_nontemporal_store(pack8(sigm4(acc[ai][0][m][0] * rs), sigm4(acc[ai][0][m][1] * rs)), (u32x4*)d); __builtin_nontemporal_store(pack8(sigm4(acc[ai][1][m][0] * rs), sigm4(acc[ai][1][m][1] * rs)), (u32x4*)(d + 128));
.LBB0_331:
	s_waitcnt lgkmcnt(0)
	v_pk_mul_f32 v[62:63], v[62:63], v[66:67] op_sel_hi:[1,0]
	v_lshlrev_b64 v[68:69], 13, v[142:143]
	v_mul_f32_e32 v62, 0xbfb8aa3b, v62
	v_exp_f32_e32 v67, v62
	v_mul_f32_e32 v62, 0xbfb8aa3b, v63
	v_exp_f32_e32 v72, v62
	v_lshl_add_u64 v[68:69], s[26:27], 0, v[68:69]
	v_pk_mul_f32 v[58:59], v[58:59], v[66:67] op_sel_hi:[1,0]
	v_pk_mul_f32 v[62:63], v[64:65], v[66:67] op_sel_hi:[1,0]
	v_mul_f32_e32 v58, 0xbfb8aa3b, v58
	v_add_f32_e32 v64, 1.0, v67
	v_exp_f32_e32 v67, v58
	v_mul_f32_e32 v58, 0xbfb8aa3b, v59
	v_add_f32_e32 v65, 1.0, v72
	v_exp_f32_e32 v72, v58
	v_pk_mul_f32 v[58:59], v[60:61], v[66:67] op_sel_hi:[1,0]
	v_mul_f32_e32 v62, 0xbfb8aa3b, v62
	v_mul_f32_e32 v63, 0xbfb8aa3b, v63
	v_mul_f32_e32 v58, 0xbfb8aa3b, v58
	v_exp_f32_e32 v62, v62
	v_exp_f32_e32 v63, v63
	v_exp_f32_e32 v58, v58
	v_mul_f32_e32 v59, 0xbfb8aa3b, v59
	v_exp_f32_e32 v59, v59
	v_add_f32_e32 v62, 1.0, v62
	v_add_f32_e32 v63, 1.0, v63
	v_add_f32_e32 v58, 1.0, v58
	v_rcp_f32_e32 v62, v62
	v_rcp_f32_e32 v63, v63
	v_add_f32_e32 v60, 1.0, v67
	v_add_f32_e32 v61, 1.0, v72
	v_rcp_f32_e32 v67, v58
	v_add_f32_e32 v58, 1.0, v59
	v_rcp_f32_e32 v64, v64
	v_rcp_f32_e32 v65, v65
	v_rcp_f32_e32 v60, v60
	v_rcp_f32_e32 v61, v61
	v_rcp_f32_e32 v72, v58
	v_lshl_add_u64 v[68:69], v[144:145], 1, v[68:69]
	s_mov_b64 s[0:1], 0x100000
	v_lshl_add_u64 v[70:71], v[68:69], 0, s[0:1]
	s_mov_b32 s0, 0x100000
	v_cvt_pk_bf16_f32 v59, v62, v63
	v_add_co_u32_e32 v62, vcc, s0, v68
	v_pk_mul_f32 v[54:55], v[54:55], v[66:67] op_sel_hi:[1,0]
	v_cvt_pk_bf16_f32 v58, v64, v65
	v_cvt_pk_bf16_f32 v60, v60, v61
	v_cvt_pk_bf16_f32 v61, v67, v72
	v_addc_co_u32_e32 v63, vcc, 0, v69, vcc
	v_mul_f32_e32 v54, 0xbfb8aa3b, v54
	global_store_dwordx4 v[62:63], v[58:61], off
	v_pk_mul_f32 v[50:51], v[50:51], v[66:67] op_sel_hi:[1,0]
	s_and_b64 vcc, exec, s[40:41]
	v_exp_f32_e32 v58, v54
	v_mul_f32_e32 v54, 0xbfb8aa3b, v55
	v_exp_f32_e32 v59, v54
	v_mul_f32_e32 v50, 0xbfb8aa3b, v50
	v_pk_mul_f32 v[54:55], v[56:57], v[66:67] op_sel_hi:[1,0]
	v_add_f32_e32 v56, 1.0, v58
	v_exp_f32_e32 v58, v50
	v_mul_f32_e32 v50, 0xbfb8aa3b, v51
	v_add_f32_e32 v57, 1.0, v59
	v_exp_f32_e32 v59, v50
	v_pk_mul_f32 v[50:51], v[52:53], v[66:67] op_sel_hi:[1,0]
	v_mul_f32_e32 v54, 0xbfb8aa3b, v54
	v_mul_f32_e32 v50, 0xbfb8aa3b, v50
	v_mul_f32_e32 v55, 0xbfb8aa3b, v55
	v_exp_f32_e32 v50, v50
	v_mul_f32_e32 v51, 0xbfb8aa3b, v51
	v_exp_f32_e32 v54, v54
	v_exp_f32_e32 v55, v55
	v_exp_f32_e32 v51, v51
	v_add_f32_e32 v50, 1.0, v50
	v_add_f32_e32 v54, 1.0, v54
	v_add_f32_e32 v55, 1.0, v55
	v_add_f32_e32 v52, 1.0, v58
	v_add_f32_e32 v53, 1.0, v59
	v_rcp_f32_e32 v58, v50
	v_add_f32_e32 v50, 1.0, v51
	v_rcp_f32_e32 v56, v56
	v_rcp_f32_e32 v57, v57
	v_rcp_f32_e32 v54, v54
	v_rcp_f32_e32 v55, v55
	v_rcp_f32_e32 v52, v52
	v_rcp_f32_e32 v53, v53
	v_rcp_f32_e32 v59, v50
	v_cvt_pk_bf16_f32 v50, v56, v57
	v_cvt_pk_bf16_f32 v51, v54, v55
	v_cvt_pk_bf16_f32 v52, v52, v53
	v_cvt_pk_bf16_f32 v53, v58, v59
	s_mov_b64 s[0:1], -1
	global_store_dwordx4 v[70:71], v[50:53], off offset:256
	s_cbranch_vccnz .LBB0_333
	s_nop 0
	v_add_u32_e32 v50, s10, v153
	v_ashrrev_i32_e32 v51, 31, v50
	v_lshlrev_b64 v[50:51], 7, v[50:51]
	v_lshl_add_u64 v[54:55], v[136:137], 0, v[50:51]
	global_load_dwordx4 v[50:53], v[54:55], off
	s_nop 0
	global_load_dwordx4 v[54:57], v[54:55], off offset:16
	s_waitcnt vmcnt(0)
	v_mov_b32_e32 v58, v50
	v_mov_b32_e32 v59, v54
	v_mov_b32_e32 v54, v51
	v_pk_add_f32 v[50:51], v[58:59], v[54:55]
	v_mov_b32_e32 v54, v52
	v_mov_b32_e32 v55, v56
	v_mov_b32_e32 v56, v53
	v_pk_add_f32 v[52:53], v[54:55], v[56:57]
	s_nop 0
	v_pk_add_f32 v[50:51], v[50:51], v[52:53]
	v_and_b32_e32 v52, 64, v190
	v_add_f32_e32 v50, v50, v51
	v_xor_b32_e32 v51, 16, v190
	v_add_u32_e32 v52, 64, v52
	v_cmp_lt_i32_e32 vcc, v51, v52
	s_nop 1
	v_cndmask_b32_e32 v51, v190, v51, vcc
	v_lshlrev_b32_e32 v51, 2, v51
	ds_bpermute_b32 v51, v51, v50
	s_waitcnt lgkmcnt(0)
	v_add_f32_e32 v50, v50, v51
	v_xor_b32_e32 v51, 32, v190
	v_cmp_lt_i32_e32 vcc, v51, v52
	s_nop 1
	v_cndmask_b32_e32 v51, v190, v51, vcc
	v_lshlrev_b32_e32 v51, 2, v51
	ds_bpermute_b32 v51, v51, v50
	s_waitcnt lgkmcnt(0)
	v_add_f32_e32 v50, v50, v51
	v_fmamk_f32 v50, v50, 0x3a000000, v187
	v_cmp_gt_f32_e32 vcc, s3, v50
	v_mul_f32_e32 v51, 0x4f800000, v50
	s_nop 0
	v_cndmask_b32_e32 v50, v50, v51, vcc
	v_sqrt_f32_e32 v51, v50
	s_nop 0
	v_add_u32_e32 v52, -1, v51
	v_fma_f32 v53, -v52, v51, v50
	v_cmp_ge_f32_e64 s[0:1], 0, v53
	v_add_u32_e32 v53, 1, v51
	s_nop 0
	v_cndmask_b32_e64 v52, v51, v52, s[0:1]
	v_fma_f32 v51, -v53, v51, v50
	v_cmp_lt_f32_e64 s[0:1], 0, v51
	s_nop 1
	v_cndmask_b32_e64 v51, v52, v53, s[0:1]
	v_mul_f32_e32 v52, 0x37800000, v51
	v_cndmask_b32_e32 v51, v51, v52, vcc
	v_cmp_class_f32_e32 vcc, v50, v188
	s_nop 1
	v_cndmask_b32_e32 v50, v51, v50, vcc
	v_div_scale_f32 v51, s[0:1], v50, v50, 1.0
	v_rcp_f32_e32 v52, v51
	s_mov_b64 s[0:1], 0
	v_fma_f32 v53, -v51, v52, 1.0
	v_fmac_f32_e32 v52, v53, v52
	v_div_scale_f32 v53, vcc, 1.0, v50, 1.0
	v_mul_f32_e32 v54, v53, v52
	v_fma_f32 v55, -v51, v54, v53
	v_fmac_f32_e32 v54, v55, v52
	v_fma_f32 v51, -v51, v54, v53
	v_div_fmas_f32 v51, v51, v52, v54
	v_div_fixup_f32 v50, v51, v50, 1.0

; __device__ __forceinline__ u32x4 pack8(const f32x4 a, const f32x4 b) { u32x4 w; w.x = cvt_pk(a[0], a[1]); w.y = cvt_pk(a[2], a[3]); w.z = cvt_pk(b[0], b[1]); w.w = cvt_pk(b[2], b[3]); return w; }
; __device__ __forceinline__ f32x4 sigm4(f32x4 v) { f32x4 o; o[0] = sigm(v[0]); o[1] = sigm(v[1]); o[2] = sigm(v[2]); o[3] = sigm(v[3]); return o; }
; template <int NP> __device__ __forceinline__ float row_rstd(const float* ss, int row, int fq, float inv_dim, float eps) {
;     float s;
;     if constexpr (NP == 32) { const f32x4 a = *(const f32x4*)(ss + (size_t)row * 32 + fq * 8), b = *(const f32x4*)(ss + (size_t)row * 32 + fq * 8 + 4); s = ((a[0] + a[1]) + (a[2] + a[3])) + ((b[0] + b[1]) + (b[2] + b[3])); }
;     else if constexpr (NP == 8) { const f32x2 a = *(const f32x2*)(ss + (size_t)row * 8 + fq * 2); s = a[0] + a[1]; }
;     else { s = ss[(size_t)row * 4 + fq]; }
;     s += __shfl_xor(s, 16); s += __shfl_xor(s, 32);
;     return 1.0f / sqrtf(s * inv_dim + eps);
;     __device__ __forceinline__ void operator()(const f32x4 (&acc)[2][2][4][2], const Unit& u, int wr, int wc, int fr, int fq) const {
;     ...
;             const int row = rowb + ai * 128 + m * 16;
;             const float rs = rs_get<32>(rc, ssx, u.pm, wr * 64 + fr + ai * 128 + m * 16, fq, 1.0f / 2048.0f, 1e-6f);
;             bf16_t* d = sg + (size_t)row * 4096 + cb;
;             __builtin_nontemporal_store(pack8(sigm4(acc[ai][0][m][0] * rs), sigm4(acc[ai][0][m][1] * rs)), (u32x4*)d); __builtin_nontemporal_store(pack8(sigm4(acc[ai][1][m][0] * rs), sigm4(acc[ai][1][m][1] * rs)), (u32x4*)(d + 128));
.LBB0_335:
	s_waitcnt lgkmcnt(0)
	v_pk_mul_f32 v[46:47], v[46:47], v[50:51] op_sel_hi:[1,0]
	v_lshlrev_b64 v[52:53], 13, v[142:143]
	v_mul_f32_e32 v46, 0xbfb8aa3b, v46
	v_exp_f32_e32 v51, v46
	v_mul_f32_e32 v46, 0xbfb8aa3b, v47
	v_exp_f32_e32 v56, v46
	v_lshl_add_u64 v[52:53], s[26:27], 0, v[52:53]
	v_pk_mul_f32 v[42:43], v[42:43], v[50:51] op_sel_hi:[1,0]
	v_pk_mul_f32 v[46:47], v[48:49], v[50:51] op_sel_hi:[1,0]
	v_mul_f32_e32 v42, 0xbfb8aa3b, v42
	v_add_f32_e32 v48, 1.0, v51
	v_exp_f32_e32 v51, v42
	v_mul_f32_e32 v42, 0xbfb8aa3b, v43
	v_add_f32_e32 v49, 1.0, v56
	v_exp_f32_e32 v56, v42
	v_pk_mul_f32 v[42:43], v[44:45], v[50:51] op_sel_hi:[1,0]
	v_mul_f32_e32 v46, 0xbfb8aa3b, v46
	v_mul_f32_e32 v47, 0xbfb8aa3b, v47
	v_mul_f32_e32 v42, 0xbfb8aa3b, v42
	v_exp_f32_e32 v46, v46
	v_exp_f32_e32 v47, v47
	v_exp_f32_e32 v42, v42
	v_mul_f32_e32 v43, 0xbfb8aa3b, v43
	v_exp_f32_e32 v43, v43
	v_add_f32_e32 v46, 1.0, v46
	v_add_f32_e32 v47, 1.0, v47
	v_add_f32_e32 v42, 1.0, v42
	v_rcp_f32_e32 v46, v46
	v_rcp_f32_e32 v47, v47
	v_add_f32_e32 v44, 1.0, v51
	v_add_f32_e32 v45, 1.0, v56
	v_rcp_f32_e32 v51, v42
	v_add_f32_e32 v42, 1.0, v43
	v_rcp_f32_e32 v48, v48
	v_rcp_f32_e32 v49, v49
	v_rcp_f32_e32 v44, v44
	v_rcp_f32_e32 v45, v45
	v_rcp_f32_e32 v56, v42
	v_lshl_add_u64 v[52:53], v[144:145], 1, v[52:53]
	s_mov_b64 s[0:1], 0x120000
	v_lshl_add_u64 v[54:55], v[52:53], 0, s[0:1]
	s_mov_b32 s0, 0x120000
	v_cvt_pk_bf16_f32 v43, v46, v47
	v_add_co_u32_e32 v46, vcc, s0, v52
	v_pk_mul_f32 v[38:39], v[38:39], v[50:51] op_sel_hi:[1,0]
	v_cvt_pk_bf16_f32 v42, v48, v49
	v_cvt_pk_bf16_f32 v44, v44, v45
	v_cvt_pk_bf16_f32 v45, v51, v56
	v_addc_co_u32_e32 v47, vcc, 0, v53, vcc
	v_mul_f32_e32 v38, 0xbfb8aa3b, v38
	global_store_dwordx4 v[46:47], v[42:45], off
	v_pk_mul_f32 v[34:35], v[34:35], v[50:51] op_sel_hi:[1,0]
	s_and_b64 vcc, exec, s[40:41]
	v_exp_f32_e32 v42, v38
	v_mul_f32_e32 v38, 0xbfb8aa3b, v39
	v_exp_f32_e32 v43, v38
	v_mul_f32_e32 v34, 0xbfb8aa3b, v34
	v_pk_mul_f32 v[38:39], v[40:41], v[50:51] op_sel_hi:[1,0]
	v_add_f32_e32 v40, 1.0, v42
	v_exp_f32_e32 v42, v34
	v_mul_f32_e32 v34, 0xbfb8aa3b, v35
	v_add_f32_e32 v41, 1.0, v43
	v_exp_f32_e32 v43, v34
	v_pk_mul_f32 v[34:35], v[36:37], v[50:51] op_sel_hi:[1,0]
	v_mul_f32_e32 v38, 0xbfb8aa3b, v38
	v_mul_f32_e32 v34, 0xbfb8aa3b, v34
	v_mul_f32_e32 v39, 0xbfb8aa3b, v39
	v_exp_f32_e32 v34, v34
	v_mul_f32_e32 v35, 0xbfb8aa3b, v35
	v_exp_f32_e32 v38, v38
	v_exp_f32_e32 v39, v39
	v_exp_f32_e32 v35, v35
	v_add_f32_e32 v34, 1.0, v34
	v_add_f32_e32 v38, 1.0, v38
	v_add_f32_e32 v39, 1.0, v39
	v_add_f32_e32 v36, 1.0, v42
	v_add_f32_e32 v37, 1.0, v43
	v_rcp_f32_e32 v42, v34
	v_add_f32_e32 v34, 1.0, v35
	v_rcp_f32_e32 v40, v40
	v_rcp_f32_e32 v41, v41
	v_rcp_f32_e32 v38, v38
	v_rcp_f32_e32 v39, v39
	v_rcp_f32_e32 v36, v36
	v_rcp_f32_e32 v37, v37
	v_rcp_f32_e32 v43, v34
	v_cvt_pk_bf16_f32 v34, v40, v41
	v_cvt_pk_bf16_f32 v35, v38, v39
	v_cvt_pk_bf16_f32 v36, v36, v37
	v_cvt_pk_bf16_f32 v37, v42, v43
	s_mov_b64 s[0:1], -1
	global_store_dwordx4 v[54:55], v[34:37], off offset:256
	s_cbranch_vccnz .LBB0_337
	s_nop 0
	v_add_u32_e32 v34, s10, v154
	v_ashrrev_i32_e32 v35, 31, v34
	v_lshlrev_b64 v[34:35], 7, v[34:35]
	v_lshl_add_u64 v[38:39], v[136:137], 0, v[34:35]
	global_load_dwordx4 v[34:37], v[38:39], off
	s_nop 0
	global_load_dwordx4 v[38:41], v[38:39], off offset:16
	s_waitcnt vmcnt(0)
	v_mov_b32_e32 v42, v34
	v_mov_b32_e32 v43, v38
	v_mov_b32_e32 v38, v35
	v_pk_add_f32 v[34:35], v[42:43], v[38:39]
	v_mov_b32_e32 v38, v36
	v_mov_b32_e32 v39, v40
	v_mov_b32_e32 v40, v37
	v_pk_add_f32 v[36:37], v[38:39], v[40:41]
	s_nop 0
	v_pk_add_f32 v[34:35], v[34:35], v[36:37]
	v_and_b32_e32 v36, 64, v190
	v_add_f32_e32 v34, v34, v35
	v_xor_b32_e32 v35, 16, v190
	v_add_u32_e32 v36, 64, v36
	v_cmp_lt_i32_e32 vcc, v35, v36
	s_nop 1
	v_cndmask_b32_e32 v35, v190, v35, vcc
	v_lshlrev_b32_e32 v35, 2, v35
	ds_bpermute_b32 v35, v35, v34
	s_waitcnt lgkmcnt(0)
	v_add_f32_e32 v34, v34, v35
	v_xor_b32_e32 v35, 32, v190
	v_cmp_lt_i32_e32 vcc, v35, v36
	s_nop 1
	v_cndmask_b32_e32 v35, v190, v35, vcc
	v_lshlrev_b32_e32 v35, 2, v35
	ds_bpermute_b32 v35, v35, v34
	s_waitcnt lgkmcnt(0)
	v_add_f32_e32 v34, v34, v35
	v_fmamk_f32 v34, v34, 0x3a000000, v187
	v_cmp_gt_f32_e32 vcc, s3, v34
	v_mul_f32_e32 v35, 0x4f800000, v34
	s_nop 0
	v_cndmask_b32_e32 v34, v34, v35, vcc
	v_sqrt_f32_e32 v35, v34
	s_nop 0
	v_add_u32_e32 v36, -1, v35
	v_fma_f32 v37, -v36, v35, v34
	v_cmp_ge_f32_e64 s[0:1], 0, v37
	v_add_u32_e32 v37, 1, v35
	s_nop 0
	v_cndmask_b32_e64 v36, v35, v36, s[0:1]
	v_fma_f32 v35, -v37, v35, v34
	v_cmp_lt_f32_e64 s[0:1], 0, v35
	s_nop 1
	v_cndmask_b32_e64 v35, v36, v37, s[0:1]
	v_mul_f32_e32 v36, 0x37800000, v35
	v_cndmask_b32_e32 v35, v35, v36, vcc
	v_cmp_class_f32_e32 vcc, v34, v188
	s_nop 1
	v_cndmask_b32_e32 v34, v35, v34, vcc
	v_div_scale_f32 v35, s[0:1], v34, v34, 1.0
	v_rcp_f32_e32 v36, v35
	s_mov_b64 s[0:1], 0
	v_fma_f32 v37, -v35, v36, 1.0
	v_fmac_f32_e32 v36, v37, v36
	v_div_scale_f32 v37, vcc, 1.0, v34, 1.0
	v_mul_f32_e32 v38, v37, v36
	v_fma_f32 v39, -v35, v38, v37
	v_fmac_f32_e32 v38, v39, v36
	v_fma_f32 v35, -v35, v38, v37
	v_div_fmas_f32 v35, v35, v36, v38
	v_div_fixup_f32 v34, v35, v34, 1.0

; __device__ __forceinline__ u32x4 pack8(const f32x4 a, const f32x4 b) { u32x4 w; w.x = cvt_pk(a[0], a[1]); w.y = cvt_pk(a[2], a[3]); w.z = cvt_pk(b[0], b[1]); w.w = cvt_pk(b[2], b[3]); return w; }
; __device__ __forceinline__ f32x4 sigm4(f32x4 v) { f32x4 o; o[0] = sigm(v[0]); o[1] = sigm(v[1]); o[2] = sigm(v[2]); o[3] = sigm(v[3]); return o; }
; template <int NP> __device__ __forceinline__ float row_rstd(const float* ss, int row, int fq, float inv_dim, float eps) {
;     float s;
;     if constexpr (NP == 32) { const f32x4 a = *(const f32x4*)(ss + (size_t)row * 32 + fq * 8), b = *(const f32x4*)(ss + (size_t)row * 32 + fq * 8 + 4); s = ((a[0] + a[1]) + (a[2] + a[3])) + ((b[0] + b[1]) + (b[2] + b[3])); }
;     else if constexpr (NP == 8) { const f32x2 a = *(const f32x2*)(ss + (size_t)row * 8 + fq * 2); s = a[0] + a[1]; }
;     else { s = ss[(size_t)row * 4 + fq]; }
;     s += __shfl_xor(s, 16); s += __shfl_xor(s, 32);
;     return 1.0f / sqrtf(s * inv_dim + eps);
;     __device__ __forceinline__ void operator()(const f32x4 (&acc)[2][2][4][2], const Unit& u, int wr, int wc, int fr, int fq) const {
;     ...
;             const int row = rowb + ai * 128 + m * 16;
;             const float rs = rs_get<32>(rc, ssx, u.pm, wr * 64 + fr + ai * 128 + m * 16, fq, 1.0f / 2048.0f, 1e-6f);
;             bf16_t* d = sg + (size_t)row * 4096 + cb;
;             __builtin_nontemporal_store(pack8(sigm4(acc[ai][0][m][0] * rs), sigm4(acc[ai][0][m][1] * rs)), (u32x4*)d); __builtin_nontemporal_store(pack8(sigm4(acc[ai][1][m][0] * rs), sigm4(acc[ai][1][m][1] * rs)), (u32x4*)(d + 128));
.LBB0_339:
	s_waitcnt lgkmcnt(0)
	v_pk_mul_f32 v[30:31], v[30:31], v[34:35] op_sel_hi:[1,0]
	v_lshlrev_b64 v[36:37], 13, v[142:143]
	v_mul_f32_e32 v30, 0xbfb8aa3b, v30
	v_exp_f32_e32 v35, v30
	v_mul_f32_e32 v30, 0xbfb8aa3b, v31
	v_exp_f32_e32 v40, v30
	v_lshl_add_u64 v[36:37], s[26:27], 0, v[36:37]
	v_pk_mul_f32 v[26:27], v[26:27], v[34:35] op_sel_hi:[1,0]
	v_pk_mul_f32 v[30:31], v[32:33], v[34:35] op_sel_hi:[1,0]
	v_mul_f32_e32 v26, 0xbfb8aa3b, v26
	v_add_f32_e32 v32, 1.0, v35
	v_exp_f32_e32 v35, v26
	v_mul_f32_e32 v26, 0xbfb8aa3b, v27
	v_add_f32_e32 v33, 1.0, v40
	v_exp_f32_e32 v40, v26
	v_pk_mul_f32 v[26:27], v[28:29], v[34:35] op_sel_hi:[1,0]
	v_mul_f32_e32 v30, 0xbfb8aa3b, v30
	v_mul_f32_e32 v31, 0xbfb8aa3b, v31
	v_mul_f32_e32 v26, 0xbfb8aa3b, v26
	v_exp_f32_e32 v30, v30
	v_exp_f32_e32 v31, v31
	v_exp_f32_e32 v26, v26
	v_mul_f32_e32 v27, 0xbfb8aa3b, v27
	v_exp_f32_e32 v27, v27
	v_add_f32_e32 v30, 1.0, v30
	v_add_f32_e32 v31, 1.0, v31
	v_add_f32_e32 v26, 1.0, v26
	v_rcp_f32_e32 v30, v30
	v_rcp_f32_e32 v31, v31
	v_add_f32_e32 v28, 1.0, v35
	v_add_f32_e32 v29, 1.0, v40
	v_rcp_f32_e32 v35, v26
	v_add_f32_e32 v26, 1.0, v27
	v_rcp_f32_e32 v32, v32
	v_rcp_f32_e32 v33, v33
	v_rcp_f32_e32 v28, v28
	v_rcp_f32_e32 v29, v29
	v_rcp_f32_e32 v40, v26
	v_lshl_add_u64 v[36:37], v[144:145], 1, v[36:37]
	s_mov_b64 s[0:1], 0x140000
	v_lshl_add_u64 v[38:39], v[36:37], 0, s[0:1]
	s_mov_b32 s0, 0x140000
	v_cvt_pk_bf16_f32 v27, v30, v31
	v_add_co_u32_e32 v30, vcc, s0, v36
	v_pk_mul_f32 v[22:23], v[22:23], v[34:35] op_sel_hi:[1,0]
	v_cvt_pk_bf16_f32 v26, v32, v33
	v_cvt_pk_bf16_f32 v28, v28, v29
	v_cvt_pk_bf16_f32 v29, v35, v40
	v_addc_co_u32_e32 v31, vcc, 0, v37, vcc
	v_mul_f32_e32 v22, 0xbfb8aa3b, v22
	global_store_dwordx4 v[30:31], v[26:29], off
	v_pk_mul_f32 v[18:19], v[18:19], v[34:35] op_sel_hi:[1,0]
	s_and_b64 vcc, exec, s[40:41]
	v_exp_f32_e32 v26, v22
	v_mul_f32_e32 v22, 0xbfb8aa3b, v23
	v_exp_f32_e32 v27, v22
	v_mul_f32_e32 v18, 0xbfb8aa3b, v18
	v_pk_mul_f32 v[22:23], v[24:25], v[34:35] op_sel_hi:[1,0]
	v_add_f32_e32 v24, 1.0, v26
	v_exp_f32_e32 v26, v18
	v_mul_f32_e32 v18, 0xbfb8aa3b, v19
	v_add_f32_e32 v25, 1.0, v27
	v_exp_f32_e32 v27, v18
	v_pk_mul_f32 v[18:19], v[20:21], v[34:35] op_sel_hi:[1,0]
	v_mul_f32_e32 v22, 0xbfb8aa3b, v22
	v_mul_f32_e32 v18, 0xbfb8aa3b, v18
	v_mul_f32_e32 v23, 0xbfb8aa3b, v23
	v_exp_f32_e32 v18, v18
	v_mul_f32_e32 v19, 0xbfb8aa3b, v19
	v_exp_f32_e32 v22, v22
	v_exp_f32_e32 v23, v23
	v_exp_f32_e32 v19, v19
	v_add_f32_e32 v18, 1.0, v18
	v_add_f32_e32 v22, 1.0, v22
	v_add_f32_e32 v23, 1.0, v23
	v_add_f32_e32 v20, 1.0, v26
	v_add_f32_e32 v21, 1.0, v27
	v_rcp_f32_e32 v26, v18
	v_add_f32_e32 v18, 1.0, v19
	v_rcp_f32_e32 v24, v24
	v_rcp_f32_e32 v25, v25
	v_rcp_f32_e32 v22, v22
	v_rcp_f32_e32 v23, v23
	v_rcp_f32_e32 v20, v20
	v_rcp_f32_e32 v21, v21
	v_rcp_f32_e32 v27, v18
	v_cvt_pk_bf16_f32 v18, v24, v25
	v_cvt_pk_bf16_f32 v19, v22, v23
	v_cvt_pk_bf16_f32 v20, v20, v21
	v_cvt_pk_bf16_f32 v21, v26, v27
	s_mov_b64 s[0:1], -1
	global_store_dwordx4 v[38:39], v[18:21], off offset:256
	s_cbranch_vccnz .LBB0_341
	s_nop 0
	v_add_u32_e32 v18, s10, v155
	v_ashrrev_i32_e32 v19, 31, v18
	v_lshlrev_b64 v[18:19], 7, v[18:19]
	v_lshl_add_u64 v[22:23], v[136:137], 0, v[18:19]
	global_load_dwordx4 v[18:21], v[22:23], off
	s_nop 0
	global_load_dwordx4 v[22:25], v[22:23], off offset:16
	s_waitcnt vmcnt(0)
	v_mov_b32_e32 v26, v18
	v_mov_b32_e32 v27, v22
	v_mov_b32_e32 v22, v19
	v_pk_add_f32 v[18:19], v[26:27], v[22:23]
	v_mov_b32_e32 v22, v20
	v_mov_b32_e32 v23, v24
	v_mov_b32_e32 v24, v21
	v_pk_add_f32 v[20:21], v[22:23], v[24:25]
	s_nop 0
	v_pk_add_f32 v[18:19], v[18:19], v[20:21]
	v_and_b32_e32 v20, 64, v190
	v_add_f32_e32 v18, v18, v19
	v_xor_b32_e32 v19, 16, v190
	v_add_u32_e32 v20, 64, v20
	v_cmp_lt_i32_e32 vcc, v19, v20
	s_nop 1
	v_cndmask_b32_e32 v19, v190, v19, vcc
	v_lshlrev_b32_e32 v19, 2, v19
	ds_bpermute_b32 v19, v19, v18
	s_waitcnt lgkmcnt(0)
	v_add_f32_e32 v18, v18, v19
	v_xor_b32_e32 v19, 32, v190
	v_cmp_lt_i32_e32 vcc, v19, v20
	s_nop 1
	v_cndmask_b32_e32 v19, v190, v19, vcc
	v_lshlrev_b32_e32 v19, 2, v19
	ds_bpermute_b32 v19, v19, v18
	s_waitcnt lgkmcnt(0)
	v_add_f32_e32 v18, v18, v19
	v_fmamk_f32 v18, v18, 0x3a000000, v187
	v_cmp_gt_f32_e32 vcc, s3, v18
	v_mul_f32_e32 v19, 0x4f800000, v18
	s_nop 0
	v_cndmask_b32_e32 v18, v18, v19, vcc
	v_sqrt_f32_e32 v19, v18
	s_nop 0
	v_add_u32_e32 v20, -1, v19
	v_fma_f32 v21, -v20, v19, v18
	v_cmp_ge_f32_e64 s[0:1], 0, v21
	v_add_u32_e32 v21, 1, v19
	s_nop 0
	v_cndmask_b32_e64 v20, v19, v20, s[0:1]
	v_fma_f32 v19, -v21, v19, v18
	v_cmp_lt_f32_e64 s[0:1], 0, v19
	s_nop 1
	v_cndmask_b32_e64 v19, v20, v21, s[0:1]
	v_mul_f32_e32 v20, 0x37800000, v19
	v_cndmask_b32_e32 v19, v19, v20, vcc
	v_cmp_class_f32_e32 vcc, v18, v188
	s_nop 1
	v_cndmask_b32_e32 v18, v19, v18, vcc
	v_div_scale_f32 v19, s[0:1], v18, v18, 1.0
	v_rcp_f32_e32 v20, v19
	s_mov_b64 s[0:1], 0
	v_fma_f32 v21, -v19, v20, 1.0
	v_fmac_f32_e32 v20, v21, v20
	v_div_scale_f32 v21, vcc, 1.0, v18, 1.0
	v_mul_f32_e32 v22, v21, v20
	v_fma_f32 v23, -v19, v22, v21
	v_fmac_f32_e32 v22, v23, v20
	v_fma_f32 v19, -v19, v22, v21
	v_div_fmas_f32 v19, v19, v20, v22
	v_div_fixup_f32 v18, v19, v18, 1.0

; __device__ __forceinline__ u32x4 pack8(const f32x4 a, const f32x4 b) { u32x4 w; w.x = cvt_pk(a[0], a[1]); w.y = cvt_pk(a[2], a[3]); w.z = cvt_pk(b[0], b[1]); w.w = cvt_pk(b[2], b[3]); return w; }
; __device__ __forceinline__ float sigm(float x) { return __builtin_amdgcn_rcpf(1.0f + __builtin_amdgcn_exp2f(x * -1.4426950408889634f)); }
; __device__ __forceinline__ f32x4 sigm4(f32x4 v) { f32x4 o; o[0] = sigm(v[0]); o[1] = sigm(v[1]); o[2] = sigm(v[2]); o[3] = sigm(v[3]); return o; }
;     __device__ __forceinline__ void operator()(const f32x4 (&acc)[2][2][4][2], const Unit& u, int wr, int wc, int fr, int fq) const {
;     ...
;             const int row = rowb + ai * 128 + m * 16;
;             const float rs = rs_get<32>(rc, ssx, u.pm, wr * 64 + fr + ai * 128 + m * 16, fq, 1.0f / 2048.0f, 1e-6f);
;             bf16_t* d = sg + (size_t)row * 4096 + cb;
;             __builtin_nontemporal_store(pack8(sigm4(acc[ai][0][m][0] * rs), sigm4(acc[ai][0][m][1] * rs)), (u32x4*)d); __builtin_nontemporal_store(pack8(sigm4(acc[ai][1][m][0] * rs), sigm4(acc[ai][1][m][1] * rs)), (u32x4*)(d + 128));
.LBB0_343:
	s_waitcnt lgkmcnt(0)
	v_pk_mul_f32 v[14:15], v[14:15], v[18:19] op_sel_hi:[1,0]
	v_lshlrev_b64 v[20:21], 13, v[142:143]
	v_mul_f32_e32 v14, 0xbfb8aa3b, v14
	v_exp_f32_e32 v19, v14
	v_mul_f32_e32 v14, 0xbfb8aa3b, v15
	v_exp_f32_e32 v24, v14
	v_lshl_add_u64 v[20:21], s[26:27], 0, v[20:21]
	v_pk_mul_f32 v[10:11], v[10:11], v[18:19] op_sel_hi:[1,0]
	v_pk_mul_f32 v[14:15], v[16:17], v[18:19] op_sel_hi:[1,0]
	v_mul_f32_e32 v10, 0xbfb8aa3b, v10
	v_add_f32_e32 v16, 1.0, v19
	v_exp_f32_e32 v19, v10
	v_mul_f32_e32 v10, 0xbfb8aa3b, v11
	v_add_f32_e32 v17, 1.0, v24
	v_exp_f32_e32 v24, v10
	v_pk_mul_f32 v[10:11], v[12:13], v[18:19] op_sel_hi:[1,0]
	v_mul_f32_e32 v14, 0xbfb8aa3b, v14
	v_mul_f32_e32 v15, 0xbfb8aa3b, v15
	v_mul_f32_e32 v10, 0xbfb8aa3b, v10
	v_exp_f32_e32 v14, v14
	v_exp_f32_e32 v15, v15
	v_exp_f32_e32 v10, v10
	v_mul_f32_e32 v11, 0xbfb8aa3b, v11
	v_exp_f32_e32 v11, v11
	v_add_f32_e32 v14, 1.0, v14
	v_add_f32_e32 v15, 1.0, v15
	v_add_f32_e32 v10, 1.0, v10
	v_rcp_f32_e32 v14, v14
	v_rcp_f32_e32 v15, v15
	v_add_f32_e32 v12, 1.0, v19
	v_add_f32_e32 v13, 1.0, v24
	v_rcp_f32_e32 v19, v10
	v_add_f32_e32 v10, 1.0, v11
	v_rcp_f32_e32 v16, v16
	v_rcp_f32_e32 v17, v17
	v_rcp_f32_e32 v12, v12
	v_rcp_f32_e32 v13, v13
	v_rcp_f32_e32 v24, v10
	v_lshl_add_u64 v[20:21], v[144:145], 1, v[20:21]
	s_mov_b64 s[0:1], 0x160000
	v_lshl_add_u64 v[22:23], v[20:21], 0, s[0:1]
	s_mov_b32 s0, 0x160000
	v_cvt_pk_bf16_f32 v11, v14, v15
	v_add_co_u32_e32 v14, vcc, s0, v20
	v_pk_mul_f32 v[6:7], v[6:7], v[18:19] op_sel_hi:[1,0]
	v_cvt_pk_bf16_f32 v10, v16, v17
	v_cvt_pk_bf16_f32 v12, v12, v13
	v_cvt_pk_bf16_f32 v13, v19, v24
	v_addc_co_u32_e32 v15, vcc, 0, v21, vcc
	v_mul_f32_e32 v6, 0xbfb8aa3b, v6
	global_store_dwordx4 v[14:15], v[10:13], off
	v_pk_mul_f32 v[2:3], v[2:3], v[18:19] op_sel_hi:[1,0]
	s_and_b64 vcc, exec, s[38:39]
	v_exp_f32_e32 v10, v6
	v_mul_f32_e32 v6, 0xbfb8aa3b, v7
	v_exp_f32_e32 v11, v6
	v_mul_f32_e32 v2, 0xbfb8aa3b, v2
	v_pk_mul_f32 v[6:7], v[8:9], v[18:19] op_sel_hi:[1,0]
	v_add_f32_e32 v8, 1.0, v10
	v_exp_f32_e32 v10, v2
	v_mul_f32_e32 v2, 0xbfb8aa3b, v3
	v_add_f32_e32 v9, 1.0, v11
	v_exp_f32_e32 v11, v2
	v_pk_mul_f32 v[2:3], v[4:5], v[18:19] op_sel_hi:[1,0]
	v_mul_f32_e32 v6, 0xbfb8aa3b, v6
	v_mul_f32_e32 v2, 0xbfb8aa3b, v2
	v_mul_f32_e32 v7, 0xbfb8aa3b, v7
	v_exp_f32_e32 v2, v2
	v_mul_f32_e32 v3, 0xbfb8aa3b, v3
	v_exp_f32_e32 v6, v6
	v_exp_f32_e32 v7, v7
	v_exp_f32_e32 v3, v3
	v_add_f32_e32 v2, 1.0, v2
	v_add_f32_e32 v6, 1.0, v6
	v_add_f32_e32 v7, 1.0, v7
	v_add_f32_e32 v4, 1.0, v10
	v_add_f32_e32 v5, 1.0, v11
	v_rcp_f32_e32 v10, v2
	v_add_f32_e32 v2, 1.0, v3
	v_rcp_f32_e32 v8, v8
	v_rcp_f32_e32 v9, v9
	v_rcp_f32_e32 v6, v6
	v_rcp_f32_e32 v7, v7
	v_rcp_f32_e32 v4, v4
	v_rcp_f32_e32 v5, v5
	v_rcp_f32_e32 v11, v2
	v_cvt_pk_bf16_f32 v2, v8, v9
	v_cvt_pk_bf16_f32 v3, v6, v7
	v_cvt_pk_bf16_f32 v4, v4, v5
	v_cvt_pk_bf16_f32 v5, v10, v11
	global_store_dwordx4 v[22:23], v[2:5], off offset:256
	s_mov_b64 s[0:1], -1
	s_cbranch_vccnz .LBB0_295
	s_andn2_b64 vcc, exec, s[24:25]
	s_cbranch_vccnz .LBB0_294
	s_barrier
	s_branch .LBB0_294
